# v115 plus nt hint on the P0 weight-transpose source loads (f32 weights are read once; keeps them from displacing x / bf16 outputs in L2)
# speedup vs baseline: 1.0105x; 1.0063x over previous
.LBB0_22:
	s_load_dwordx2 s[6:7], s[6:7], 0x0
	s_add_i32 s10, s50, 0xfffff000
	s_lshr_b32 s10, s10, 4
	s_lshl_b64 s[26:27], s[10:11], 16
	s_waitcnt lgkmcnt(0)
	s_add_u32 s6, s6, s26
	s_addc_u32 s7, s7, s27
	s_lshl_b32 s27, s50, 5
	s_lshl_b32 s26, s50, 4
	s_and_b32 s27, s27, 0x60
	s_and_b32 s26, s26, 64
	v_or_b32_e32 v130, s27, v1
	v_or_b32_e32 v132, s26, v162
	v_lshlrev_b32_e32 v174, 2, v130
	v_lshl_add_u64 v[130:131], s[6:7], 0, v[174:175]
	v_lshlrev_b32_e32 v174, 9, v132
	v_lshl_add_u64 v[158:159], v[130:131], 0, v[174:175]
	v_add_co_u32_e32 v138, vcc, s13, v158
	global_load_dwordx4 v[130:133], v[158:159], off nt
	s_nop 0
	v_addc_co_u32_e32 v139, vcc, 0, v159, vcc
	v_add_co_u32_e32 v146, vcc, s15, v158
	global_load_dwordx4 v[134:137], v[138:139], off offset:-4096 nt
	s_nop 0
	global_load_dwordx4 v[138:141], v[138:139], off nt
	v_addc_co_u32_e32 v147, vcc, 0, v159, vcc
	v_add_co_u32_e32 v154, vcc, s51, v158
	global_load_dwordx4 v[142:145], v[146:147], off offset:-4096 nt
	s_nop 0
	global_load_dwordx4 v[146:149], v[146:147], off nt
	v_addc_co_u32_e32 v155, vcc, 0, v159, vcc
	global_load_dwordx4 v[150:153], v[154:155], off offset:-4096 nt
	s_nop 0
	global_load_dwordx4 v[154:157], v[154:155], off nt
	v_add_co_u32_e32 v158, vcc, s52, v158
	v_add_u32_e32 v174, v183, v191
	s_nop 0
	v_addc_co_u32_e32 v159, vcc, 0, v159, vcc
	global_load_dwordx4 v[158:161], v[158:159], off nt
	v_add_u32_e32 v180, 0x420, v174
	v_add_u32_e32 v181, 0x428, v174
	v_add_u32_e32 v182, 0x840, v174
	v_add_u32_e32 v184, 0x848, v174
	v_add_u32_e32 v196, 0xc60, v174
	v_add_u32_e32 v197, 0xc68, v174
	v_add_u32_e32 v199, 0x1080, v174
	v_add_u32_e32 v200, 0x1088, v174
	v_add_u32_e32 v201, 0x14a0, v174
	v_add_u32_e32 v202, 0x14a8, v174
	v_add_u32_e32 v203, 0x18c0, v174
	v_add_u32_e32 v204, 0x18c8, v174
	v_add_u32_e32 v205, 0x1ce0, v174
	v_add_u32_e32 v206, 0x1ce8, v174
	s_lshl_b32 s6, s10, 8
	s_lshl_b32 s7, s28, 7
	s_or_b32 s6, s6, s7
	s_or_b32 s6, s6, s27
	s_lshl_b32 s10, s26, 1
	s_waitcnt vmcnt(7)
	ds_write2_b32 v174, v130, v131 offset1:1
	ds_write2_b32 v174, v132, v133 offset0:2 offset1:3
	s_waitcnt vmcnt(6)
	ds_write2_b32 v180, v134, v135 offset1:1
	ds_write2_b32 v181, v136, v137 offset1:1
	s_waitcnt vmcnt(5)
	ds_write2_b32 v182, v138, v139 offset1:1
	ds_write2_b32 v184, v140, v141 offset1:1
	s_waitcnt vmcnt(4)
	ds_write2_b32 v196, v142, v143 offset1:1
	ds_write2_b32 v197, v144, v145 offset1:1
	s_waitcnt vmcnt(3)
	ds_write2_b32 v199, v146, v147 offset1:1
	ds_write2_b32 v200, v148, v149 offset1:1
	s_waitcnt vmcnt(2)
	ds_write2_b32 v201, v150, v151 offset1:1
	ds_write2_b32 v202, v152, v153 offset1:1
	s_waitcnt vmcnt(1)
	ds_write2_b32 v203, v154, v155 offset1:1
	ds_write2_b32 v204, v156, v157 offset1:1
	s_waitcnt vmcnt(0)
	ds_write2_b32 v205, v158, v159 offset1:1
	ds_write2_b32 v206, v160, v161 offset1:1
	s_waitcnt lgkmcnt(0)
	ds_read2_b32 v[130:131], v188 offset1:33
	s_waitcnt lgkmcnt(0)
	v_cvt_pk_bf16_f32 v130, v130, v131
	ds_read2_b32 v[132:133], v188 offset0:66 offset1:99
	v_or_b32_e32 v174, s6, v162
	s_waitcnt lgkmcnt(0)
	v_cvt_pk_bf16_f32 v131, v132, v133
	ds_read2_b32 v[132:133], v188 offset0:132 offset1:165
	v_lshl_add_u64 v[136:137], v[164:165], 0, s[10:11]
	v_lshlrev_b64 v[138:139], 8, v[174:175]
	s_waitcnt lgkmcnt(0)
	v_cvt_pk_bf16_f32 v132, v132, v133
	ds_read2_b32 v[134:135], v188 offset0:198 offset1:231
	s_waitcnt lgkmcnt(0)
	v_cvt_pk_bf16_f32 v133, v134, v135
	v_lshl_add_u64 v[138:139], v[136:137], 0, v[138:139]
	ds_read2_b32 v[134:135], v188 offset0:8 offset1:41
	global_store_dwordx4 v[138:139], v[130:133], off
	v_or_b32_e32 v174, s6, v185
	v_lshlrev_b64 v[138:139], 8, v[174:175]
	s_waitcnt lgkmcnt(0)
	v_cvt_pk_bf16_f32 v130, v134, v135
	ds_read2_b32 v[132:133], v188 offset0:74 offset1:107
	s_waitcnt lgkmcnt(0)
	v_cvt_pk_bf16_f32 v131, v132, v133
	ds_read2_b32 v[132:133], v188 offset0:140 offset1:173
	s_waitcnt lgkmcnt(0)
	v_cvt_pk_bf16_f32 v132, v132, v133
	ds_read2_b32 v[134:135], v188 offset0:206 offset1:239
	s_waitcnt lgkmcnt(0)
	v_cvt_pk_bf16_f32 v133, v134, v135
	v_lshl_add_u64 v[138:139], v[136:137], 0, v[138:139]
	ds_read2_b32 v[134:135], v188 offset0:16 offset1:49
	global_store_dwordx4 v[138:139], v[130:133], off
	v_or_b32_e32 v174, s6, v186
	v_lshlrev_b64 v[138:139], 8, v[174:175]
	s_waitcnt lgkmcnt(0)
	v_cvt_pk_bf16_f32 v130, v134, v135
	ds_read2_b32 v[132:133], v188 offset0:82 offset1:115
	s_waitcnt lgkmcnt(0)
	v_cvt_pk_bf16_f32 v131, v132, v133
	ds_read2_b32 v[132:133], v188 offset0:148 offset1:181
	s_waitcnt lgkmcnt(0)
	v_cvt_pk_bf16_f32 v132, v132, v133
	ds_read2_b32 v[134:135], v188 offset0:214 offset1:247
	s_waitcnt lgkmcnt(0)
	v_cvt_pk_bf16_f32 v133, v134, v135
	v_lshl_add_u64 v[138:139], v[136:137], 0, v[138:139]
	ds_read2_b32 v[134:135], v188 offset0:24 offset1:57
	global_store_dwordx4 v[138:139], v[130:133], off
	v_or_b32_e32 v174, s6, v187
	v_lshlrev_b64 v[138:139], 8, v[174:175]
	s_waitcnt lgkmcnt(0)
	v_cvt_pk_bf16_f32 v130, v134, v135
	ds_read2_b32 v[132:133], v188 offset0:90 offset1:123
	s_waitcnt lgkmcnt(0)
	v_cvt_pk_bf16_f32 v131, v132, v133
	ds_read2_b32 v[132:133], v188 offset0:156 offset1:189
	s_waitcnt lgkmcnt(0)
	v_cvt_pk_bf16_f32 v132, v132, v133
	ds_read2_b32 v[134:135], v188 offset0:222 offset1:255
	s_waitcnt lgkmcnt(0)
	v_cvt_pk_bf16_f32 v133, v134, v135
	v_lshl_add_u64 v[134:135], v[136:137], 0, v[138:139]
	global_store_dwordx4 v[134:135], v[130:133], off
	s_waitcnt lgkmcnt(0)
	s_mov_b64 s[6:7], 0
.LBB0_23:
	s_and_b64 vcc, exec, s[6:7]
	s_cbranch_vccz .LBB0_25
	s_mov_b64 s[6:7], s[0:1]
	s_load_dwordx2 s[26:27], s[6:7], 0x88
	s_lshl_b32 s6, s50, 1
	s_add_i32 s6, s6, 0x7fffe400
	s_and_b32 s7, s6, 0x7fffffc0
	s_lshl_b32 s6, s50, 5
	s_and_b32 s6, s6, 0x3e0
	v_or_b32_e32 v130, s6, v1
	v_or_b32_e32 v158, s7, v162
	v_lshlrev_b32_e32 v174, 2, v130
	s_waitcnt lgkmcnt(0)
	v_lshl_add_u64 v[160:161], s[26:27], 0, v[174:175]
	v_or_b32_e32 v174, 8, v158
	v_lshlrev_b64 v[132:133], 12, v[174:175]
	v_or_b32_e32 v174, 16, v158
	v_lshlrev_b64 v[138:139], 12, v[174:175]
	v_or_b32_e32 v174, 24, v158
	v_lshlrev_b64 v[140:141], 12, v[174:175]
	v_or_b32_e32 v174, 32, v158
	v_mov_b32_e32 v159, v175
	v_lshlrev_b64 v[146:147], 12, v[174:175]
	v_or_b32_e32 v174, 40, v158
	v_lshlrev_b64 v[130:131], 12, v[158:159]
	v_lshlrev_b64 v[148:149], 12, v[174:175]
	v_lshl_add_u64 v[130:131], v[160:161], 0, v[130:131]
	v_lshl_add_u64 v[134:135], v[160:161], 0, v[132:133]
	v_lshl_add_u64 v[138:139], v[160:161], 0, v[138:139]
	v_lshl_add_u64 v[142:143], v[160:161], 0, v[140:141]
	v_lshl_add_u64 v[146:147], v[160:161], 0, v[146:147]
	v_lshl_add_u64 v[150:151], v[160:161], 0, v[148:149]
	global_load_dwordx4 v[130:133], v[130:131], off nt
	s_nop 0
	global_load_dwordx4 v[134:137], v[134:135], off nt
	s_nop 0
	global_load_dwordx4 v[138:141], v[138:139], off nt
	s_nop 0
	global_load_dwordx4 v[142:145], v[142:143], off nt
	s_nop 0
	global_load_dwordx4 v[146:149], v[146:147], off nt
	s_nop 0
	global_load_dwordx4 v[150:153], v[150:151], off nt
	v_or_b32_e32 v174, 48, v158
	v_lshlrev_b64 v[154:155], 12, v[174:175]
	v_lshl_add_u64 v[154:155], v[160:161], 0, v[154:155]
	v_or_b32_e32 v174, 56, v158
	global_load_dwordx4 v[154:157], v[154:155], off nt
	v_lshlrev_b64 v[158:159], 12, v[174:175]
	v_lshl_add_u64 v[158:159], v[160:161], 0, v[158:159]
	global_load_dwordx4 v[158:161], v[158:159], off nt
	v_add_u32_e32 v174, v183, v191
	v_add_u32_e32 v180, 0x420, v174
	v_add_u32_e32 v181, 0x428, v174
	v_add_u32_e32 v182, 0x840, v174
	v_add_u32_e32 v184, 0x848, v174
	v_add_u32_e32 v196, 0xc60, v174
	v_add_u32_e32 v197, 0xc68, v174
	v_add_u32_e32 v199, 0x1080, v174
	v_add_u32_e32 v200, 0x1088, v174
	v_add_u32_e32 v201, 0x14a0, v174
	v_add_u32_e32 v202, 0x14a8, v174
	v_add_u32_e32 v203, 0x18c0, v174
	v_add_u32_e32 v204, 0x18c8, v174
	v_add_u32_e32 v205, 0x1ce0, v174
	v_add_u32_e32 v206, 0x1ce8, v174
	s_lshl_b32 s10, s7, 1
	s_waitcnt vmcnt(7)
	ds_write2_b32 v174, v130, v131 offset1:1
	ds_write2_b32 v174, v132, v133 offset0:2 offset1:3
	s_waitcnt vmcnt(6)
	ds_write2_b32 v180, v134, v135 offset1:1
	ds_write2_b32 v181, v136, v137 offset1:1
	s_waitcnt vmcnt(5)
	ds_write2_b32 v182, v138, v139 offset1:1
	ds_write2_b32 v184, v140, v141 offset1:1
	s_waitcnt vmcnt(4)
	ds_write2_b32 v196, v142, v143 offset1:1
	ds_write2_b32 v197, v144, v145 offset1:1
	s_waitcnt vmcnt(3)
	ds_write2_b32 v199, v146, v147 offset1:1
	ds_write2_b32 v200, v148, v149 offset1:1
	s_waitcnt vmcnt(2)
	ds_write2_b32 v201, v150, v151 offset1:1
	ds_write2_b32 v202, v152, v153 offset1:1
	s_waitcnt vmcnt(1)
	ds_write2_b32 v203, v154, v155 offset1:1
	ds_write2_b32 v204, v156, v157 offset1:1
	s_waitcnt vmcnt(0)
	ds_write2_b32 v205, v158, v159 offset1:1
	ds_write2_b32 v206, v160, v161 offset1:1
	s_waitcnt lgkmcnt(0)
	ds_read2_b32 v[130:131], v188 offset1:33
	s_waitcnt lgkmcnt(0)
	v_cvt_pk_bf16_f32 v130, v130, v131
	ds_read2_b32 v[132:133], v188 offset0:66 offset1:99
	v_or_b32_e32 v138, s6, v162
	s_waitcnt lgkmcnt(0)
	v_cvt_pk_bf16_f32 v131, v132, v133
	ds_read2_b32 v[132:133], v188 offset0:132 offset1:165
	v_lshl_add_u64 v[136:137], v[166:167], 0, s[10:11]
	v_lshlrev_b32_e32 v174, 11, v138
	s_waitcnt lgkmcnt(0)
	v_cvt_pk_bf16_f32 v132, v132, v133
	ds_read2_b32 v[134:135], v188 offset0:198 offset1:231
	s_waitcnt lgkmcnt(0)
	v_cvt_pk_bf16_f32 v133, v134, v135
	v_lshl_add_u64 v[138:139], v[136:137], 0, v[174:175]
	ds_read2_b32 v[134:135], v188 offset0:8 offset1:41
	global_store_dwordx4 v[138:139], v[130:133], off
	v_or_b32_e32 v138, s6, v185
	v_lshlrev_b32_e32 v174, 11, v138
	s_waitcnt lgkmcnt(0)
	v_cvt_pk_bf16_f32 v130, v134, v135
	ds_read2_b32 v[132:133], v188 offset0:74 offset1:107
	s_waitcnt lgkmcnt(0)
	v_cvt_pk_bf16_f32 v131, v132, v133
	ds_read2_b32 v[132:133], v188 offset0:140 offset1:173
	s_waitcnt lgkmcnt(0)
	v_cvt_pk_bf16_f32 v132, v132, v133
	ds_read2_b32 v[134:135], v188 offset0:206 offset1:239
	s_waitcnt lgkmcnt(0)
	v_cvt_pk_bf16_f32 v133, v134, v135
	v_lshl_add_u64 v[138:139], v[136:137], 0, v[174:175]
	ds_read2_b32 v[134:135], v188 offset0:16 offset1:49
	global_store_dwordx4 v[138:139], v[130:133], off
	v_or_b32_e32 v138, s6, v186
	v_lshlrev_b32_e32 v174, 11, v138
	s_waitcnt lgkmcnt(0)
	v_cvt_pk_bf16_f32 v130, v134, v135
	ds_read2_b32 v[132:133], v188 offset0:82 offset1:115
	s_waitcnt lgkmcnt(0)
	v_cvt_pk_bf16_f32 v131, v132, v133
	ds_read2_b32 v[132:133], v188 offset0:148 offset1:181
	s_waitcnt lgkmcnt(0)
	v_cvt_pk_bf16_f32 v132, v132, v133
	ds_read2_b32 v[134:135], v188 offset0:214 offset1:247
	s_waitcnt lgkmcnt(0)
	v_cvt_pk_bf16_f32 v133, v134, v135
	v_lshl_add_u64 v[138:139], v[136:137], 0, v[174:175]
	ds_read2_b32 v[134:135], v188 offset0:24 offset1:57
	global_store_dwordx4 v[138:139], v[130:133], off
	s_waitcnt lgkmcnt(0)
	s_nop 0
	v_cvt_pk_bf16_f32 v130, v134, v135
	ds_read2_b32 v[132:133], v188 offset0:90 offset1:123
	s_waitcnt lgkmcnt(0)
	v_cvt_pk_bf16_f32 v131, v132, v133
	ds_read2_b32 v[132:133], v188 offset0:156 offset1:189
	s_waitcnt lgkmcnt(0)
	v_cvt_pk_bf16_f32 v132, v132, v133
	v_or_b32_e32 v133, s6, v187
	ds_read2_b32 v[134:135], v188 offset0:222 offset1:255
	v_lshlrev_b32_e32 v174, 11, v133
	s_waitcnt lgkmcnt(0)
	v_cvt_pk_bf16_f32 v133, v134, v135
	v_lshl_add_u64 v[134:135], v[136:137], 0, v[174:175]
	global_store_dwordx4 v[134:135], v[130:133], off
	s_waitcnt lgkmcnt(0)

.LBB0_26:
	s_andn2_b64 vcc, exec, s[6:7]
	s_cbranch_vccnz .LBB0_38
	s_lshl_b32 s28, s50, 5
	s_mov_b64 s[6:7], s[0:1]
	s_and_b32 s10, s50, 0xfc0
	s_and_b32 s46, s28, 0x7e0
	s_addk_i32 s10, 0xf600
	v_or_b32_e32 v130, s46, v1
	s_load_dwordx2 s[6:7], s[6:7], 0x78
	s_cmpk_lt_u32 s46, 0x400
	v_lshrrev_b32_e32 v131, 1, v130
	s_cselect_b64 vcc, -1, 0
	s_and_b32 s28, s28, 0x380
	v_and_b32_e32 v131, 60, v131
	v_or3_b32 v131, s28, v131, v189
	v_cndmask_b32_e32 v130, v130, v131, vcc
	v_or_b32_e32 v136, s10, v162
	v_lshlrev_b32_e32 v174, 2, v130
	s_waitcnt lgkmcnt(0)
	v_lshl_add_u64 v[130:131], s[6:7], 0, v[174:175]
	v_mov_b32_e32 v174, v136
	v_or_b32_e32 v134, 8, v136
	v_mov_b32_e32 v135, v175
	v_lshlrev_b64 v[132:133], 13, v[174:175]
	v_lshlrev_b64 v[134:135], 13, v[134:135]
	s_mov_b64 s[26:27], s[0:1]
	v_lshl_add_u64 v[132:133], v[130:131], 0, v[132:133]
	v_lshl_add_u64 v[134:135], v[130:131], 0, v[134:135]
	global_load_dwordx4 v[158:161], v[132:133], off nt
	global_load_dwordx4 v[154:157], v[134:135], off nt
	v_or_b32_e32 v132, 16, v136
	v_mov_b32_e32 v133, v175
	v_or_b32_e32 v134, 24, v136
	v_mov_b32_e32 v135, v175
	v_lshlrev_b64 v[132:133], 13, v[132:133]
	v_lshlrev_b64 v[134:135], 13, v[134:135]
	v_lshl_add_u64 v[132:133], v[130:131], 0, v[132:133]
	v_lshl_add_u64 v[134:135], v[130:131], 0, v[134:135]
	global_load_dwordx4 v[150:153], v[132:133], off nt
	global_load_dwordx4 v[146:149], v[134:135], off nt
	v_or_b32_e32 v132, 32, v136
	v_mov_b32_e32 v133, v175
	v_or_b32_e32 v134, 40, v136
	v_mov_b32_e32 v135, v175
	v_lshlrev_b64 v[132:133], 13, v[132:133]
	v_lshlrev_b64 v[134:135], 13, v[134:135]
	v_lshl_add_u64 v[132:133], v[130:131], 0, v[132:133]
	v_lshl_add_u64 v[134:135], v[130:131], 0, v[134:135]
	global_load_dwordx4 v[142:145], v[132:133], off nt
	global_load_dwordx4 v[138:141], v[134:135], off nt
	v_or_b32_e32 v132, 48, v136
	v_mov_b32_e32 v133, v175
	v_or_b32_e32 v134, 56, v136
	v_mov_b32_e32 v135, v175
	v_lshlrev_b64 v[132:133], 13, v[132:133]
	v_lshlrev_b64 v[134:135], 13, v[134:135]
	v_lshl_add_u64 v[132:133], v[130:131], 0, v[132:133]
	v_lshl_add_u64 v[130:131], v[130:131], 0, v[134:135]
	global_load_dwordx4 v[134:137], v[132:133], off nt
	s_nop 0
	global_load_dwordx4 v[130:133], v[130:131], off nt
	s_load_dwordx2 s[26:27], s[26:27], 0x70
	v_mov_b32_e32 v182, 1.0
	v_add_u32_e32 v180, s10, v162
	v_mov_b32_e32 v184, 1.0
	s_waitcnt lgkmcnt(0)
	s_cmp_lg_u64 s[26:27], 0
	s_cselect_b64 s[28:29], -1, 0
	s_cmp_eq_u64 s[26:27], 0
	s_cbranch_scc1 .LBB0_29
	v_lshl_add_u64 v[196:197], v[174:175], 2, s[26:27]
	v_mov_b32_e32 v181, v175
	global_load_dword v174, v[196:197], off
	v_lshl_add_u64 v[196:197], v[180:181], 2, s[26:27]
	global_load_dword v184, v[196:197], off offset:32
	s_waitcnt vmcnt(1)
	v_pk_mul_f32 v[158:159], v[158:159], v[174:175] op_sel_hi:[1,0]
	v_pk_mul_f32 v[160:161], v[160:161], v[174:175] op_sel_hi:[1,0]

.LBB0_39:
	s_andn2_b64 vcc, exec, s[6:7]
	s_cbranch_vccnz .LBB0_51
	s_lshl_b32 s28, s50, 5
	s_mov_b64 s[6:7], s[0:1]
	s_and_b32 s10, s50, 0xfc0
	s_and_b32 s46, s28, 0x7e0
	s_addk_i32 s10, 0xfa00
	v_or_b32_e32 v130, s46, v1
	s_load_dwordx2 s[6:7], s[6:7], 0x60
	s_cmpk_lt_u32 s46, 0x400
	v_lshrrev_b32_e32 v131, 1, v130
	s_cselect_b64 vcc, -1, 0
	s_and_b32 s28, s28, 0x380
	v_and_b32_e32 v131, 60, v131
	v_or3_b32 v131, s28, v131, v189
	v_cndmask_b32_e32 v130, v130, v131, vcc
	v_or_b32_e32 v136, s10, v162
	v_lshlrev_b32_e32 v174, 2, v130
	s_waitcnt lgkmcnt(0)
	v_lshl_add_u64 v[130:131], s[6:7], 0, v[174:175]
	v_mov_b32_e32 v174, v136
	v_or_b32_e32 v134, 8, v136
	v_mov_b32_e32 v135, v175
	v_lshlrev_b64 v[132:133], 13, v[174:175]
	v_lshlrev_b64 v[134:135], 13, v[134:135]
	s_mov_b64 s[26:27], s[0:1]
	v_lshl_add_u64 v[132:133], v[130:131], 0, v[132:133]
	v_lshl_add_u64 v[134:135], v[130:131], 0, v[134:135]
	global_load_dwordx4 v[158:161], v[132:133], off nt
	global_load_dwordx4 v[154:157], v[134:135], off nt
	v_or_b32_e32 v132, 16, v136
	v_mov_b32_e32 v133, v175
	v_or_b32_e32 v134, 24, v136
	v_mov_b32_e32 v135, v175
	v_lshlrev_b64 v[132:133], 13, v[132:133]
	v_lshlrev_b64 v[134:135], 13, v[134:135]
	v_lshl_add_u64 v[132:133], v[130:131], 0, v[132:133]
	v_lshl_add_u64 v[134:135], v[130:131], 0, v[134:135]
	global_load_dwordx4 v[150:153], v[132:133], off nt
	global_load_dwordx4 v[146:149], v[134:135], off nt
	v_or_b32_e32 v132, 32, v136
	v_mov_b32_e32 v133, v175
	v_or_b32_e32 v134, 40, v136
	v_mov_b32_e32 v135, v175
	v_lshlrev_b64 v[132:133], 13, v[132:133]
	v_lshlrev_b64 v[134:135], 13, v[134:135]
	v_lshl_add_u64 v[132:133], v[130:131], 0, v[132:133]
	v_lshl_add_u64 v[134:135], v[130:131], 0, v[134:135]
	global_load_dwordx4 v[142:145], v[132:133], off nt
	global_load_dwordx4 v[138:141], v[134:135], off nt
	v_or_b32_e32 v132, 48, v136
	v_mov_b32_e32 v133, v175
	v_or_b32_e32 v134, 56, v136
	v_mov_b32_e32 v135, v175
	v_lshlrev_b64 v[132:133], 13, v[132:133]
	v_lshlrev_b64 v[134:135], 13, v[134:135]
	v_lshl_add_u64 v[132:133], v[130:131], 0, v[132:133]
	v_lshl_add_u64 v[130:131], v[130:131], 0, v[134:135]
	global_load_dwordx4 v[134:137], v[132:133], off nt
	s_nop 0
	global_load_dwordx4 v[130:133], v[130:131], off nt
	s_load_dwordx2 s[26:27], s[26:27], 0x58
	v_mov_b32_e32 v182, 1.0
	v_add_u32_e32 v180, s10, v162
	v_mov_b32_e32 v184, 1.0
	s_waitcnt lgkmcnt(0)
	s_cmp_lg_u64 s[26:27], 0
	s_cselect_b64 s[28:29], -1, 0
	s_cmp_eq_u64 s[26:27], 0
	s_cbranch_scc1 .LBB0_42
	v_lshl_add_u64 v[196:197], v[174:175], 2, s[26:27]
	v_mov_b32_e32 v181, v175
	global_load_dword v174, v[196:197], off
	v_lshl_add_u64 v[196:197], v[180:181], 2, s[26:27]
	global_load_dword v184, v[196:197], off offset:32
	s_waitcnt vmcnt(1)
	v_pk_mul_f32 v[158:159], v[158:159], v[174:175] op_sel_hi:[1,0]
	v_pk_mul_f32 v[160:161], v[160:161], v[174:175] op_sel_hi:[1,0]

.LBB0_52:
	s_andn2_b64 vcc, exec, s[6:7]
	s_cbranch_vccnz .LBB0_54
	s_mov_b64 s[6:7], s[0:1]
	s_load_dwordx2 s[26:27], s[6:7], 0x50
	s_lshl_b32 s6, s50, 1
	s_add_i32 s6, s6, 0x7ffff800
	s_and_b32 s7, s6, 0x7fffffc0
	s_lshl_b32 s6, s50, 5
	s_and_b32 s6, s6, 0x3e0
	v_or_b32_e32 v130, s6, v1
	v_or_b32_e32 v158, s7, v162
	v_lshlrev_b32_e32 v174, 2, v130
	s_waitcnt lgkmcnt(0)
	v_lshl_add_u64 v[160:161], s[26:27], 0, v[174:175]
	v_or_b32_e32 v174, 8, v158
	v_lshlrev_b64 v[132:133], 12, v[174:175]
	v_or_b32_e32 v174, 16, v158
	v_lshlrev_b64 v[138:139], 12, v[174:175]
	v_or_b32_e32 v174, 24, v158
	v_lshlrev_b64 v[140:141], 12, v[174:175]
	v_or_b32_e32 v174, 32, v158
	v_mov_b32_e32 v159, v175
	v_lshlrev_b64 v[146:147], 12, v[174:175]
	v_or_b32_e32 v174, 40, v158
	v_lshlrev_b64 v[130:131], 12, v[158:159]
	v_lshlrev_b64 v[148:149], 12, v[174:175]
	v_lshl_add_u64 v[130:131], v[160:161], 0, v[130:131]
	v_lshl_add_u64 v[134:135], v[160:161], 0, v[132:133]
	v_lshl_add_u64 v[138:139], v[160:161], 0, v[138:139]
	v_lshl_add_u64 v[142:143], v[160:161], 0, v[140:141]
	v_lshl_add_u64 v[146:147], v[160:161], 0, v[146:147]
	v_lshl_add_u64 v[150:151], v[160:161], 0, v[148:149]
	global_load_dwordx4 v[130:133], v[130:131], off nt
	s_nop 0
	global_load_dwordx4 v[134:137], v[134:135], off nt
	s_nop 0
	global_load_dwordx4 v[138:141], v[138:139], off nt
	s_nop 0
	global_load_dwordx4 v[142:145], v[142:143], off nt
	s_nop 0
	global_load_dwordx4 v[146:149], v[146:147], off nt
	s_nop 0
	global_load_dwordx4 v[150:153], v[150:151], off nt
	v_or_b32_e32 v174, 48, v158
	v_lshlrev_b64 v[154:155], 12, v[174:175]
	v_lshl_add_u64 v[154:155], v[160:161], 0, v[154:155]
	v_or_b32_e32 v174, 56, v158
	global_load_dwordx4 v[154:157], v[154:155], off nt
	v_lshlrev_b64 v[158:159], 12, v[174:175]
	v_lshl_add_u64 v[158:159], v[160:161], 0, v[158:159]
	global_load_dwordx4 v[158:161], v[158:159], off nt
	v_add_u32_e32 v174, v183, v191
	v_add_u32_e32 v180, 0x420, v174
	v_add_u32_e32 v181, 0x428, v174
	v_add_u32_e32 v182, 0x840, v174
	v_add_u32_e32 v184, 0x848, v174
	v_add_u32_e32 v196, 0xc60, v174
	v_add_u32_e32 v197, 0xc68, v174
	v_add_u32_e32 v199, 0x1080, v174
	v_add_u32_e32 v200, 0x1088, v174
	v_add_u32_e32 v201, 0x14a0, v174
	v_add_u32_e32 v202, 0x14a8, v174
	v_add_u32_e32 v203, 0x18c0, v174
	v_add_u32_e32 v204, 0x18c8, v174
	v_add_u32_e32 v205, 0x1ce0, v174
	v_add_u32_e32 v206, 0x1ce8, v174
	s_lshl_b32 s10, s7, 1
	s_waitcnt vmcnt(7)
	ds_write2_b32 v174, v130, v131 offset1:1
	ds_write2_b32 v174, v132, v133 offset0:2 offset1:3
	s_waitcnt vmcnt(6)
	ds_write2_b32 v180, v134, v135 offset1:1
	ds_write2_b32 v181, v136, v137 offset1:1
	s_waitcnt vmcnt(5)
	ds_write2_b32 v182, v138, v139 offset1:1
	ds_write2_b32 v184, v140, v141 offset1:1
	s_waitcnt vmcnt(4)
	ds_write2_b32 v196, v142, v143 offset1:1
	ds_write2_b32 v197, v144, v145 offset1:1
	s_waitcnt vmcnt(3)
	ds_write2_b32 v199, v146, v147 offset1:1
	ds_write2_b32 v200, v148, v149 offset1:1
	s_waitcnt vmcnt(2)
	ds_write2_b32 v201, v150, v151 offset1:1
	ds_write2_b32 v202, v152, v153 offset1:1
	s_waitcnt vmcnt(1)
	ds_write2_b32 v203, v154, v155 offset1:1
	ds_write2_b32 v204, v156, v157 offset1:1
	s_waitcnt vmcnt(0)
	ds_write2_b32 v205, v158, v159 offset1:1
	ds_write2_b32 v206, v160, v161 offset1:1
	s_waitcnt lgkmcnt(0)
	ds_read2_b32 v[130:131], v188 offset1:33
	s_waitcnt lgkmcnt(0)
	v_cvt_pk_bf16_f32 v130, v130, v131
	ds_read2_b32 v[132:133], v188 offset0:66 offset1:99
	v_or_b32_e32 v138, s6, v162
	s_waitcnt lgkmcnt(0)
	v_cvt_pk_bf16_f32 v131, v132, v133
	ds_read2_b32 v[132:133], v188 offset0:132 offset1:165
	v_lshl_add_u64 v[136:137], v[170:171], 0, s[10:11]
	v_lshlrev_b32_e32 v174, 11, v138
	s_waitcnt lgkmcnt(0)
	v_cvt_pk_bf16_f32 v132, v132, v133
	ds_read2_b32 v[134:135], v188 offset0:198 offset1:231
	s_waitcnt lgkmcnt(0)
	v_cvt_pk_bf16_f32 v133, v134, v135
	v_lshl_add_u64 v[138:139], v[136:137], 0, v[174:175]
	ds_read2_b32 v[134:135], v188 offset0:8 offset1:41
	global_store_dwordx4 v[138:139], v[130:133], off
	v_or_b32_e32 v138, s6, v185
	v_lshlrev_b32_e32 v174, 11, v138
	s_waitcnt lgkmcnt(0)
	v_cvt_pk_bf16_f32 v130, v134, v135
	ds_read2_b32 v[132:133], v188 offset0:74 offset1:107
	s_waitcnt lgkmcnt(0)
	v_cvt_pk_bf16_f32 v131, v132, v133
	ds_read2_b32 v[132:133], v188 offset0:140 offset1:173
	s_waitcnt lgkmcnt(0)
	v_cvt_pk_bf16_f32 v132, v132, v133
	ds_read2_b32 v[134:135], v188 offset0:206 offset1:239
	s_waitcnt lgkmcnt(0)
	v_cvt_pk_bf16_f32 v133, v134, v135
	v_lshl_add_u64 v[138:139], v[136:137], 0, v[174:175]
	ds_read2_b32 v[134:135], v188 offset0:16 offset1:49
	global_store_dwordx4 v[138:139], v[130:133], off
	v_or_b32_e32 v138, s6, v186
	v_lshlrev_b32_e32 v174, 11, v138
	s_waitcnt lgkmcnt(0)
	v_cvt_pk_bf16_f32 v130, v134, v135
	ds_read2_b32 v[132:133], v188 offset0:82 offset1:115
	s_waitcnt lgkmcnt(0)
	v_cvt_pk_bf16_f32 v131, v132, v133
	ds_read2_b32 v[132:133], v188 offset0:148 offset1:181
	s_waitcnt lgkmcnt(0)
	v_cvt_pk_bf16_f32 v132, v132, v133
	ds_read2_b32 v[134:135], v188 offset0:214 offset1:247
	s_waitcnt lgkmcnt(0)
	v_cvt_pk_bf16_f32 v133, v134, v135
	v_lshl_add_u64 v[138:139], v[136:137], 0, v[174:175]
	ds_read2_b32 v[134:135], v188 offset0:24 offset1:57
	global_store_dwordx4 v[138:139], v[130:133], off
	s_waitcnt lgkmcnt(0)
	s_nop 0
	v_cvt_pk_bf16_f32 v130, v134, v135
	ds_read2_b32 v[132:133], v188 offset0:90 offset1:123
	s_waitcnt lgkmcnt(0)
	v_cvt_pk_bf16_f32 v131, v132, v133
	ds_read2_b32 v[132:133], v188 offset0:156 offset1:189
	s_waitcnt lgkmcnt(0)
	v_cvt_pk_bf16_f32 v132, v132, v133
	v_or_b32_e32 v133, s6, v187
	ds_read2_b32 v[134:135], v188 offset0:222 offset1:255
	v_lshlrev_b32_e32 v174, 11, v133
	s_waitcnt lgkmcnt(0)
	v_cvt_pk_bf16_f32 v133, v134, v135
	v_lshl_add_u64 v[134:135], v[136:137], 0, v[174:175]
	global_store_dwordx4 v[134:135], v[130:133], off
	s_waitcnt lgkmcnt(0)

.LBB0_55:
	s_andn2_b64 vcc, exec, s[6:7]
	s_cbranch_vccnz .LBB0_67
	s_ashr_i32 s10, s50, 31
	s_mov_b64 s[6:7], s[0:1]
	s_lshr_b32 s10, s10, 26
	s_add_i32 s10, s50, s10
	s_load_dwordx2 s[6:7], s[6:7], 0x10
	s_and_b32 s26, s10, 0xffffffc0
	s_sub_i32 s10, s50, s26
	s_lshl_b32 s10, s10, 5
	v_or_b32_e32 v180, s26, v162
	v_or_b32_e32 v130, s10, v1
	v_or_b32_e32 v134, 8, v180
	v_ashrrev_i32_e32 v131, 31, v130
	v_ashrrev_i32_e32 v181, 31, v180
	v_ashrrev_i32_e32 v135, 31, v134
	s_waitcnt lgkmcnt(0)
	v_lshl_add_u64 v[130:131], v[130:131], 2, s[6:7]
	v_lshlrev_b64 v[132:133], 13, v[180:181]
	v_lshlrev_b64 v[134:135], 13, v[134:135]
	s_mov_b64 s[28:29], s[0:1]
	v_lshl_add_u64 v[132:133], v[130:131], 0, v[132:133]
	v_lshl_add_u64 v[134:135], v[130:131], 0, v[134:135]
	global_load_dwordx4 v[158:161], v[132:133], off nt
	global_load_dwordx4 v[154:157], v[134:135], off nt
	v_or_b32_e32 v132, 16, v180
	v_or_b32_e32 v134, 24, v180
	v_ashrrev_i32_e32 v133, 31, v132
	v_ashrrev_i32_e32 v135, 31, v134
	v_lshlrev_b64 v[132:133], 13, v[132:133]
	v_lshlrev_b64 v[134:135], 13, v[134:135]
	v_lshl_add_u64 v[132:133], v[130:131], 0, v[132:133]
	v_lshl_add_u64 v[134:135], v[130:131], 0, v[134:135]
	global_load_dwordx4 v[150:153], v[132:133], off nt
	global_load_dwordx4 v[146:149], v[134:135], off nt
	v_or_b32_e32 v132, 32, v180
	v_or_b32_e32 v134, 40, v180
	v_ashrrev_i32_e32 v133, 31, v132
	v_ashrrev_i32_e32 v135, 31, v134
	v_lshlrev_b64 v[132:133], 13, v[132:133]
	v_lshlrev_b64 v[134:135], 13, v[134:135]
	v_lshl_add_u64 v[132:133], v[130:131], 0, v[132:133]
	v_lshl_add_u64 v[134:135], v[130:131], 0, v[134:135]
	global_load_dwordx4 v[142:145], v[132:133], off nt
	global_load_dwordx4 v[138:141], v[134:135], off nt
	v_or_b32_e32 v132, 48, v180
	v_or_b32_e32 v134, 56, v180
	v_ashrrev_i32_e32 v133, 31, v132
	v_ashrrev_i32_e32 v135, 31, v134
	v_lshlrev_b64 v[132:133], 13, v[132:133]
	v_lshlrev_b64 v[134:135], 13, v[134:135]
	v_lshl_add_u64 v[132:133], v[130:131], 0, v[132:133]
	v_lshl_add_u64 v[130:131], v[130:131], 0, v[134:135]
	global_load_dwordx4 v[134:137], v[132:133], off nt
	s_nop 0
	global_load_dwordx4 v[130:133], v[130:131], off nt
	s_load_dwordx2 s[28:29], s[28:29], 0x8
	v_mov_b32_e32 v174, 1.0
	v_mov_b32_e32 v182, 1.0
	s_waitcnt lgkmcnt(0)
	s_cmp_lg_u64 s[28:29], 0
	s_cselect_b64 s[46:47], -1, 0
	s_cmp_eq_u64 s[28:29], 0
	s_cbranch_scc1 .LBB0_58
	s_ashr_i32 s27, s26, 31
	v_lshl_add_u64 v[180:181], v[180:181], 2, s[28:29]
	v_lshl_add_u64 v[196:197], s[26:27], 0, v[162:163]
	global_load_dword v180, v[180:181], off
	v_lshl_add_u64 v[196:197], v[196:197], 2, s[28:29]
	global_load_dword v182, v[196:197], off offset:32
	s_waitcnt vmcnt(1)
	v_pk_mul_f32 v[158:159], v[158:159], v[180:181] op_sel_hi:[1,0]
	v_pk_mul_f32 v[160:161], v[160:161], v[180:181] op_sel_hi:[1,0]

.LBB0_101:
	s_load_dwordx2 s[4:5], s[4:5], 0x0
	s_add_i32 s6, s50, 0xfffff000
	s_lshr_b32 s6, s6, 4
	s_lshl_b64 s[10:11], s[6:7], 16
	s_waitcnt lgkmcnt(0)
	s_add_u32 s4, s4, s10
	s_addc_u32 s5, s5, s11
	s_and_b32 s11, s18, 0x60
	s_and_b32 s10, s20, 64
	v_or_b32_e32 v2, s11, v1
	v_or_b32_e32 v4, s10, v162
	v_lshlrev_b32_e32 v34, 2, v2
	v_lshl_add_u64 v[2:3], s[4:5], 0, v[34:35]
	v_lshlrev_b32_e32 v34, 9, v4
	v_lshl_add_u64 v[30:31], v[2:3], 0, v[34:35]
	v_add_co_u32_e32 v14, vcc, s24, v30
	global_load_dwordx4 v[2:5], v[30:31], off nt
	s_nop 0
	v_addc_co_u32_e32 v15, vcc, 0, v31, vcc
	v_add_co_u32_e32 v22, vcc, s25, v30
	global_load_dwordx4 v[6:9], v[14:15], off offset:-4096 nt
	global_load_dwordx4 v[10:13], v[14:15], off nt
	v_addc_co_u32_e32 v23, vcc, 0, v31, vcc
	v_add_co_u32_e32 v32, vcc, s26, v30
	global_load_dwordx4 v[14:17], v[22:23], off offset:-4096 nt
	global_load_dwordx4 v[18:21], v[22:23], off nt
	v_addc_co_u32_e32 v33, vcc, 0, v31, vcc
	global_load_dwordx4 v[22:25], v[32:33], off offset:-4096 nt
	global_load_dwordx4 v[26:29], v[32:33], off nt
	v_add_co_u32_e32 v30, vcc, s27, v30
	s_lshl_b32 s4, s6, 8
	s_nop 0
	v_addc_co_u32_e32 v31, vcc, 0, v31, vcc
	global_load_dwordx4 v[30:33], v[30:31], off nt
	s_lshl_b32 s5, s12, 7
	s_or_b32 s4, s4, s5
	s_or_b32 s4, s4, s11
	s_lshl_b32 s6, s10, 1
	v_or_b32_e32 v34, s4, v162
	s_waitcnt vmcnt(7)
	ds_write2_b32 v39, v2, v3 offset1:1
	ds_write2_b32 v39, v4, v5 offset0:2 offset1:3
	s_waitcnt vmcnt(6)
	ds_write2_b32 v41, v6, v7 offset1:1
	ds_write2_b32 v42, v8, v9 offset1:1
	s_waitcnt vmcnt(5)
	ds_write2_b32 v43, v10, v11 offset1:1
	ds_write2_b32 v44, v12, v13 offset1:1
	s_waitcnt vmcnt(4)
	ds_write2_b32 v45, v14, v15 offset1:1
	ds_write2_b32 v46, v16, v17 offset1:1
	s_waitcnt vmcnt(3)
	ds_write2_b32 v47, v18, v19 offset1:1
	ds_write2_b32 v48, v20, v21 offset1:1
	s_waitcnt vmcnt(2)
	ds_write2_b32 v49, v22, v23 offset1:1
	ds_write2_b32 v50, v24, v25 offset1:1
	s_waitcnt vmcnt(1)
	ds_write2_b32 v51, v26, v27 offset1:1
	ds_write2_b32 v52, v28, v29 offset1:1
	s_waitcnt vmcnt(0)
	ds_write2_b32 v53, v30, v31 offset1:1
	ds_write2_b32 v54, v32, v33 offset1:1
	s_waitcnt lgkmcnt(0)
	ds_read2_b32 v[2:3], v188 offset1:33
	s_waitcnt lgkmcnt(0)
	v_cvt_pk_bf16_f32 v2, v2, v3
	ds_read2_b32 v[4:5], v188 offset0:66 offset1:99
	s_waitcnt lgkmcnt(0)
	v_cvt_pk_bf16_f32 v3, v4, v5
	ds_read2_b32 v[4:5], v188 offset0:132 offset1:165
	v_lshl_add_u64 v[8:9], v[164:165], 0, s[6:7]
	v_lshlrev_b64 v[10:11], 8, v[34:35]
	s_waitcnt lgkmcnt(0)
	v_cvt_pk_bf16_f32 v4, v4, v5
	ds_read2_b32 v[6:7], v188 offset0:198 offset1:231
	s_waitcnt lgkmcnt(0)
	v_cvt_pk_bf16_f32 v5, v6, v7
	v_lshl_add_u64 v[10:11], v[8:9], 0, v[10:11]
	ds_read2_b32 v[6:7], v188 offset0:8 offset1:41
	global_store_dwordx4 v[10:11], v[2:5], off
	v_or_b32_e32 v34, s4, v185
	v_lshlrev_b64 v[10:11], 8, v[34:35]
	s_waitcnt lgkmcnt(0)
	v_cvt_pk_bf16_f32 v2, v6, v7
	ds_read2_b32 v[4:5], v188 offset0:74 offset1:107
	s_waitcnt lgkmcnt(0)
	v_cvt_pk_bf16_f32 v3, v4, v5
	ds_read2_b32 v[4:5], v188 offset0:140 offset1:173
	s_waitcnt lgkmcnt(0)
	v_cvt_pk_bf16_f32 v4, v4, v5
	ds_read2_b32 v[6:7], v188 offset0:206 offset1:239
	s_waitcnt lgkmcnt(0)
	v_cvt_pk_bf16_f32 v5, v6, v7
	v_lshl_add_u64 v[10:11], v[8:9], 0, v[10:11]
	ds_read2_b32 v[6:7], v188 offset0:16 offset1:49
	global_store_dwordx4 v[10:11], v[2:5], off
	v_or_b32_e32 v34, s4, v186
	v_lshlrev_b64 v[10:11], 8, v[34:35]
	s_waitcnt lgkmcnt(0)
	v_cvt_pk_bf16_f32 v2, v6, v7
	ds_read2_b32 v[4:5], v188 offset0:82 offset1:115
	s_waitcnt lgkmcnt(0)
	v_cvt_pk_bf16_f32 v3, v4, v5
	ds_read2_b32 v[4:5], v188 offset0:148 offset1:181
	s_waitcnt lgkmcnt(0)
	v_cvt_pk_bf16_f32 v4, v4, v5
	ds_read2_b32 v[6:7], v188 offset0:214 offset1:247
	s_waitcnt lgkmcnt(0)
	v_cvt_pk_bf16_f32 v5, v6, v7
	v_lshl_add_u64 v[10:11], v[8:9], 0, v[10:11]
	ds_read2_b32 v[6:7], v188 offset0:24 offset1:57
	global_store_dwordx4 v[10:11], v[2:5], off
	v_or_b32_e32 v34, s4, v187
	v_lshlrev_b64 v[10:11], 8, v[34:35]
	s_waitcnt lgkmcnt(0)
	v_cvt_pk_bf16_f32 v2, v6, v7
	ds_read2_b32 v[4:5], v188 offset0:90 offset1:123
	s_waitcnt lgkmcnt(0)
	v_cvt_pk_bf16_f32 v3, v4, v5
	ds_read2_b32 v[4:5], v188 offset0:156 offset1:189
	s_waitcnt lgkmcnt(0)
	v_cvt_pk_bf16_f32 v4, v4, v5
	ds_read2_b32 v[6:7], v188 offset0:222 offset1:255
	s_waitcnt lgkmcnt(0)
	v_cvt_pk_bf16_f32 v5, v6, v7
	v_lshl_add_u64 v[6:7], v[8:9], 0, v[10:11]
	global_store_dwordx4 v[6:7], v[2:5], off
	s_waitcnt lgkmcnt(0)
	s_mov_b64 s[4:5], 0
.LBB0_102:
	s_and_b64 vcc, exec, s[4:5]
	s_cbranch_vccz .LBB0_104
	s_mov_b64 s[4:5], s[0:1]
	s_load_dwordx2 s[4:5], s[4:5], 0x88
	s_and_b32 s10, s18, 0x3e0
	s_and_b32 s6, s22, 0x7fffffc0
	v_or_b32_e32 v2, s10, v1
	v_or_b32_e32 v30, s6, v162
	v_lshlrev_b32_e32 v34, 2, v2
	v_mov_b32_e32 v31, v35
	s_waitcnt lgkmcnt(0)
	v_lshl_add_u64 v[32:33], s[4:5], 0, v[34:35]
	v_lshlrev_b64 v[2:3], 12, v[30:31]
	v_or_b32_e32 v34, 8, v30
	v_lshl_add_u64 v[10:11], v[32:33], 0, v[2:3]
	v_lshlrev_b64 v[2:3], 12, v[34:35]
	v_or_b32_e32 v34, 16, v30
	v_lshl_add_u64 v[12:13], v[32:33], 0, v[2:3]
	global_load_dwordx4 v[2:5], v[10:11], off nt
	global_load_dwordx4 v[6:9], v[12:13], off nt
	v_lshlrev_b64 v[10:11], 12, v[34:35]
	v_or_b32_e32 v34, 24, v30
	v_lshl_add_u64 v[18:19], v[32:33], 0, v[10:11]
	v_lshlrev_b64 v[10:11], 12, v[34:35]
	v_or_b32_e32 v34, 32, v30
	v_lshl_add_u64 v[20:21], v[32:33], 0, v[10:11]
	global_load_dwordx4 v[10:13], v[18:19], off nt
	global_load_dwordx4 v[14:17], v[20:21], off nt
	v_lshlrev_b64 v[18:19], 12, v[34:35]
	v_or_b32_e32 v34, 40, v30
	v_lshl_add_u64 v[26:27], v[32:33], 0, v[18:19]
	v_lshlrev_b64 v[18:19], 12, v[34:35]
	v_lshl_add_u64 v[28:29], v[32:33], 0, v[18:19]
	global_load_dwordx4 v[18:21], v[26:27], off nt
	global_load_dwordx4 v[22:25], v[28:29], off nt
	v_or_b32_e32 v34, 48, v30
	v_lshlrev_b64 v[26:27], 12, v[34:35]
	v_lshl_add_u64 v[26:27], v[32:33], 0, v[26:27]
	v_or_b32_e32 v34, 56, v30
	global_load_dwordx4 v[26:29], v[26:27], off nt
	v_lshlrev_b64 v[30:31], 12, v[34:35]
	v_lshl_add_u64 v[30:31], v[32:33], 0, v[30:31]
	global_load_dwordx4 v[30:33], v[30:31], off nt
	s_lshl_b32 s6, s6, 1
	s_waitcnt vmcnt(7)
	ds_write2_b32 v39, v2, v3 offset1:1
	ds_write2_b32 v39, v4, v5 offset0:2 offset1:3
	s_waitcnt vmcnt(6)
	ds_write2_b32 v41, v6, v7 offset1:1
	ds_write2_b32 v42, v8, v9 offset1:1
	s_waitcnt vmcnt(5)
	ds_write2_b32 v43, v10, v11 offset1:1
	ds_write2_b32 v44, v12, v13 offset1:1
	s_waitcnt vmcnt(4)
	ds_write2_b32 v45, v14, v15 offset1:1
	ds_write2_b32 v46, v16, v17 offset1:1
	s_waitcnt vmcnt(3)
	ds_write2_b32 v47, v18, v19 offset1:1
	ds_write2_b32 v48, v20, v21 offset1:1
	s_waitcnt vmcnt(2)
	ds_write2_b32 v49, v22, v23 offset1:1
	ds_write2_b32 v50, v24, v25 offset1:1
	s_waitcnt vmcnt(1)
	ds_write2_b32 v51, v26, v27 offset1:1
	ds_write2_b32 v52, v28, v29 offset1:1
	s_waitcnt vmcnt(0)
	ds_write2_b32 v53, v30, v31 offset1:1
	ds_write2_b32 v54, v32, v33 offset1:1
	s_waitcnt lgkmcnt(0)
	ds_read2_b32 v[2:3], v188 offset1:33
	s_waitcnt lgkmcnt(0)
	v_cvt_pk_bf16_f32 v2, v2, v3
	ds_read2_b32 v[4:5], v188 offset0:66 offset1:99
	v_or_b32_e32 v10, s10, v162
	s_waitcnt lgkmcnt(0)
	v_cvt_pk_bf16_f32 v3, v4, v5
	ds_read2_b32 v[4:5], v188 offset0:132 offset1:165
	v_lshl_add_u64 v[8:9], v[166:167], 0, s[6:7]
	v_lshlrev_b32_e32 v34, 11, v10
	s_waitcnt lgkmcnt(0)
	v_cvt_pk_bf16_f32 v4, v4, v5
	ds_read2_b32 v[6:7], v188 offset0:198 offset1:231
	s_waitcnt lgkmcnt(0)
	v_cvt_pk_bf16_f32 v5, v6, v7
	v_lshl_add_u64 v[10:11], v[8:9], 0, v[34:35]
	ds_read2_b32 v[6:7], v188 offset0:8 offset1:41
	global_store_dwordx4 v[10:11], v[2:5], off
	v_or_b32_e32 v10, s10, v185
	v_lshlrev_b32_e32 v34, 11, v10
	s_waitcnt lgkmcnt(0)
	v_cvt_pk_bf16_f32 v2, v6, v7
	ds_read2_b32 v[4:5], v188 offset0:74 offset1:107
	s_waitcnt lgkmcnt(0)
	v_cvt_pk_bf16_f32 v3, v4, v5
	ds_read2_b32 v[4:5], v188 offset0:140 offset1:173
	s_waitcnt lgkmcnt(0)
	v_cvt_pk_bf16_f32 v4, v4, v5
	ds_read2_b32 v[6:7], v188 offset0:206 offset1:239
	s_waitcnt lgkmcnt(0)
	v_cvt_pk_bf16_f32 v5, v6, v7
	v_lshl_add_u64 v[10:11], v[8:9], 0, v[34:35]
	ds_read2_b32 v[6:7], v188 offset0:16 offset1:49
	global_store_dwordx4 v[10:11], v[2:5], off
	v_or_b32_e32 v10, s10, v186
	v_lshlrev_b32_e32 v34, 11, v10
	s_waitcnt lgkmcnt(0)
	v_cvt_pk_bf16_f32 v2, v6, v7
	ds_read2_b32 v[4:5], v188 offset0:82 offset1:115
	s_waitcnt lgkmcnt(0)
	v_cvt_pk_bf16_f32 v3, v4, v5
	ds_read2_b32 v[4:5], v188 offset0:148 offset1:181
	s_waitcnt lgkmcnt(0)
	v_cvt_pk_bf16_f32 v4, v4, v5
	ds_read2_b32 v[6:7], v188 offset0:214 offset1:247
	s_waitcnt lgkmcnt(0)
	v_cvt_pk_bf16_f32 v5, v6, v7
	v_lshl_add_u64 v[10:11], v[8:9], 0, v[34:35]
	ds_read2_b32 v[6:7], v188 offset0:24 offset1:57
	global_store_dwordx4 v[10:11], v[2:5], off
	s_waitcnt lgkmcnt(0)
	s_nop 0
	v_cvt_pk_bf16_f32 v2, v6, v7
	ds_read2_b32 v[4:5], v188 offset0:90 offset1:123
	s_waitcnt lgkmcnt(0)
	v_cvt_pk_bf16_f32 v3, v4, v5
	ds_read2_b32 v[4:5], v188 offset0:156 offset1:189
	s_waitcnt lgkmcnt(0)
	v_cvt_pk_bf16_f32 v4, v4, v5
	v_or_b32_e32 v5, s10, v187
	ds_read2_b32 v[6:7], v188 offset0:222 offset1:255
	v_lshlrev_b32_e32 v34, 11, v5
	s_waitcnt lgkmcnt(0)
	v_cvt_pk_bf16_f32 v5, v6, v7
	v_lshl_add_u64 v[6:7], v[8:9], 0, v[34:35]
	global_store_dwordx4 v[6:7], v[2:5], off
	s_waitcnt lgkmcnt(0)

.LBB0_105:
	s_andn2_b64 vcc, exec, s[4:5]
	s_cbranch_vccnz .LBB0_117
	s_mov_b64 s[4:5], s[0:1]
	s_and_b32 s6, s50, 0xfc0
	s_and_b32 s14, s18, 0x7e0
	s_addk_i32 s6, 0xf600
	v_or_b32_e32 v2, s14, v1
	s_load_dwordx2 s[4:5], s[4:5], 0x78
	s_cmpk_lt_u32 s14, 0x400
	v_lshrrev_b32_e32 v3, 1, v2
	s_cselect_b64 vcc, -1, 0
	s_and_b32 s12, s18, 0x380
	v_and_b32_e32 v3, 60, v3
	v_or3_b32 v3, s12, v3, v189
	v_cndmask_b32_e32 v2, v2, v3, vcc
	v_or_b32_e32 v8, s6, v162
	v_lshlrev_b32_e32 v34, 2, v2
	s_waitcnt lgkmcnt(0)
	v_lshl_add_u64 v[2:3], s[4:5], 0, v[34:35]
	v_mov_b32_e32 v34, v8
	v_lshlrev_b64 v[4:5], 13, v[34:35]
	v_or_b32_e32 v6, 8, v8
	v_mov_b32_e32 v7, v35
	s_mov_b64 s[10:11], s[0:1]
	v_lshl_add_u64 v[4:5], v[2:3], 0, v[4:5]
	v_lshlrev_b64 v[6:7], 13, v[6:7]
	v_lshl_add_u64 v[6:7], v[2:3], 0, v[6:7]
	global_load_dwordx4 v[30:33], v[4:5], off nt
	global_load_dwordx4 v[26:29], v[6:7], off nt
	v_or_b32_e32 v4, 16, v8
	v_mov_b32_e32 v5, v35
	v_lshlrev_b64 v[4:5], 13, v[4:5]
	v_or_b32_e32 v6, 24, v8
	v_mov_b32_e32 v7, v35
	v_lshl_add_u64 v[4:5], v[2:3], 0, v[4:5]
	v_lshlrev_b64 v[6:7], 13, v[6:7]
	v_lshl_add_u64 v[6:7], v[2:3], 0, v[6:7]
	global_load_dwordx4 v[22:25], v[4:5], off nt
	global_load_dwordx4 v[18:21], v[6:7], off nt
	v_or_b32_e32 v4, 32, v8
	v_mov_b32_e32 v5, v35
	v_lshlrev_b64 v[4:5], 13, v[4:5]
	v_or_b32_e32 v6, 40, v8
	v_mov_b32_e32 v7, v35
	v_lshl_add_u64 v[4:5], v[2:3], 0, v[4:5]
	v_lshlrev_b64 v[6:7], 13, v[6:7]
	v_lshl_add_u64 v[6:7], v[2:3], 0, v[6:7]
	global_load_dwordx4 v[14:17], v[4:5], off nt
	global_load_dwordx4 v[10:13], v[6:7], off nt
	v_or_b32_e32 v4, 48, v8
	v_mov_b32_e32 v5, v35
	v_lshlrev_b64 v[4:5], 13, v[4:5]
	v_lshl_add_u64 v[36:37], v[2:3], 0, v[4:5]
	v_or_b32_e32 v4, 56, v8
	v_mov_b32_e32 v5, v35
	v_lshlrev_b64 v[4:5], 13, v[4:5]
	v_lshl_add_u64 v[56:57], v[2:3], 0, v[4:5]
	global_load_dwordx4 v[6:9], v[36:37], off nt
	global_load_dwordx4 v[2:5], v[56:57], off nt
	s_load_dwordx2 s[10:11], s[10:11], 0x70
	v_mov_b32_e32 v38, 1.0
	v_add_u32_e32 v36, s6, v162
	v_mov_b32_e32 v40, 1.0
	s_waitcnt lgkmcnt(0)
	s_cmp_lg_u64 s[10:11], 0
	s_cselect_b64 s[12:13], -1, 0
	s_cmp_eq_u64 s[10:11], 0
	s_cbranch_scc1 .LBB0_108
	v_lshl_add_u64 v[56:57], v[34:35], 2, s[10:11]
	v_mov_b32_e32 v37, v35
	global_load_dword v34, v[56:57], off
	v_lshl_add_u64 v[56:57], v[36:37], 2, s[10:11]
	global_load_dword v40, v[56:57], off offset:32
	s_waitcnt vmcnt(1)
	v_pk_mul_f32 v[30:31], v[30:31], v[34:35] op_sel_hi:[1,0]
	v_pk_mul_f32 v[32:33], v[32:33], v[34:35] op_sel_hi:[1,0]

.LBB0_118:
	s_andn2_b64 vcc, exec, s[4:5]
	s_cbranch_vccnz .LBB0_130
	s_mov_b64 s[4:5], s[0:1]
	s_and_b32 s6, s50, 0xfc0
	s_and_b32 s14, s18, 0x7e0
	s_addk_i32 s6, 0xfa00
	v_or_b32_e32 v2, s14, v1
	s_load_dwordx2 s[4:5], s[4:5], 0x60
	s_cmpk_lt_u32 s14, 0x400
	v_lshrrev_b32_e32 v3, 1, v2
	s_cselect_b64 vcc, -1, 0
	s_and_b32 s12, s18, 0x380
	v_and_b32_e32 v3, 60, v3
	v_or3_b32 v3, s12, v3, v189
	v_cndmask_b32_e32 v2, v2, v3, vcc
	v_or_b32_e32 v8, s6, v162
	v_lshlrev_b32_e32 v34, 2, v2
	s_waitcnt lgkmcnt(0)
	v_lshl_add_u64 v[2:3], s[4:5], 0, v[34:35]
	v_mov_b32_e32 v34, v8
	v_lshlrev_b64 v[4:5], 13, v[34:35]
	v_or_b32_e32 v6, 8, v8
	v_mov_b32_e32 v7, v35
	s_mov_b64 s[10:11], s[0:1]
	v_lshl_add_u64 v[4:5], v[2:3], 0, v[4:5]
	v_lshlrev_b64 v[6:7], 13, v[6:7]
	v_lshl_add_u64 v[6:7], v[2:3], 0, v[6:7]
	global_load_dwordx4 v[30:33], v[4:5], off nt
	global_load_dwordx4 v[26:29], v[6:7], off nt
	v_or_b32_e32 v4, 16, v8
	v_mov_b32_e32 v5, v35
	v_lshlrev_b64 v[4:5], 13, v[4:5]
	v_or_b32_e32 v6, 24, v8
	v_mov_b32_e32 v7, v35
	v_lshl_add_u64 v[4:5], v[2:3], 0, v[4:5]
	v_lshlrev_b64 v[6:7], 13, v[6:7]
	v_lshl_add_u64 v[6:7], v[2:3], 0, v[6:7]
	global_load_dwordx4 v[22:25], v[4:5], off nt
	global_load_dwordx4 v[18:21], v[6:7], off nt
	v_or_b32_e32 v4, 32, v8
	v_mov_b32_e32 v5, v35
	v_lshlrev_b64 v[4:5], 13, v[4:5]
	v_or_b32_e32 v6, 40, v8
	v_mov_b32_e32 v7, v35
	v_lshl_add_u64 v[4:5], v[2:3], 0, v[4:5]
	v_lshlrev_b64 v[6:7], 13, v[6:7]
	v_lshl_add_u64 v[6:7], v[2:3], 0, v[6:7]
	global_load_dwordx4 v[14:17], v[4:5], off nt
	global_load_dwordx4 v[10:13], v[6:7], off nt
	v_or_b32_e32 v4, 48, v8
	v_mov_b32_e32 v5, v35
	v_lshlrev_b64 v[4:5], 13, v[4:5]
	v_lshl_add_u64 v[36:37], v[2:3], 0, v[4:5]
	v_or_b32_e32 v4, 56, v8
	v_mov_b32_e32 v5, v35
	v_lshlrev_b64 v[4:5], 13, v[4:5]
	v_lshl_add_u64 v[56:57], v[2:3], 0, v[4:5]
	global_load_dwordx4 v[6:9], v[36:37], off nt
	global_load_dwordx4 v[2:5], v[56:57], off nt
	s_load_dwordx2 s[10:11], s[10:11], 0x58
	v_mov_b32_e32 v38, 1.0
	v_add_u32_e32 v36, s6, v162
	v_mov_b32_e32 v40, 1.0
	s_waitcnt lgkmcnt(0)
	s_cmp_lg_u64 s[10:11], 0
	s_cselect_b64 s[12:13], -1, 0
	s_cmp_eq_u64 s[10:11], 0
	s_cbranch_scc1 .LBB0_121
	v_lshl_add_u64 v[56:57], v[34:35], 2, s[10:11]
	v_mov_b32_e32 v37, v35
	global_load_dword v34, v[56:57], off
	v_lshl_add_u64 v[56:57], v[36:37], 2, s[10:11]
	global_load_dword v40, v[56:57], off offset:32
	s_waitcnt vmcnt(1)
	v_pk_mul_f32 v[30:31], v[30:31], v[34:35] op_sel_hi:[1,0]
	v_pk_mul_f32 v[32:33], v[32:33], v[34:35] op_sel_hi:[1,0]

.LBB0_131:
	s_andn2_b64 vcc, exec, s[4:5]
	s_cbranch_vccnz .LBB0_133
	s_mov_b64 s[4:5], s[0:1]
	s_load_dwordx2 s[4:5], s[4:5], 0x50
	s_add_i32 s6, s22, 0x1400
	s_and_b32 s10, s18, 0x3e0
	s_and_b32 s6, s6, 0x7fffffc0
	v_or_b32_e32 v2, s10, v1
	v_or_b32_e32 v30, s6, v162
	v_lshlrev_b32_e32 v34, 2, v2
	v_mov_b32_e32 v31, v35
	s_waitcnt lgkmcnt(0)
	v_lshl_add_u64 v[32:33], s[4:5], 0, v[34:35]
	v_lshlrev_b64 v[2:3], 12, v[30:31]
	v_or_b32_e32 v34, 8, v30
	v_lshl_add_u64 v[10:11], v[32:33], 0, v[2:3]
	v_lshlrev_b64 v[2:3], 12, v[34:35]
	v_or_b32_e32 v34, 16, v30
	v_lshl_add_u64 v[12:13], v[32:33], 0, v[2:3]
	global_load_dwordx4 v[2:5], v[10:11], off nt
	global_load_dwordx4 v[6:9], v[12:13], off nt
	v_lshlrev_b64 v[10:11], 12, v[34:35]
	v_or_b32_e32 v34, 24, v30
	v_lshl_add_u64 v[18:19], v[32:33], 0, v[10:11]
	v_lshlrev_b64 v[10:11], 12, v[34:35]
	v_or_b32_e32 v34, 32, v30
	v_lshl_add_u64 v[20:21], v[32:33], 0, v[10:11]
	global_load_dwordx4 v[10:13], v[18:19], off nt
	global_load_dwordx4 v[14:17], v[20:21], off nt
	v_lshlrev_b64 v[18:19], 12, v[34:35]
	v_or_b32_e32 v34, 40, v30
	v_lshl_add_u64 v[26:27], v[32:33], 0, v[18:19]
	v_lshlrev_b64 v[18:19], 12, v[34:35]
	v_lshl_add_u64 v[28:29], v[32:33], 0, v[18:19]
	global_load_dwordx4 v[18:21], v[26:27], off nt
	global_load_dwordx4 v[22:25], v[28:29], off nt
	v_or_b32_e32 v34, 48, v30
	v_lshlrev_b64 v[26:27], 12, v[34:35]
	v_lshl_add_u64 v[26:27], v[32:33], 0, v[26:27]
	v_or_b32_e32 v34, 56, v30
	global_load_dwordx4 v[26:29], v[26:27], off nt
	v_lshlrev_b64 v[30:31], 12, v[34:35]
	v_lshl_add_u64 v[30:31], v[32:33], 0, v[30:31]
	global_load_dwordx4 v[30:33], v[30:31], off nt
	s_lshl_b32 s6, s6, 1
	s_waitcnt vmcnt(7)
	ds_write2_b32 v39, v2, v3 offset1:1
	ds_write2_b32 v39, v4, v5 offset0:2 offset1:3
	s_waitcnt vmcnt(6)
	ds_write2_b32 v41, v6, v7 offset1:1
	ds_write2_b32 v42, v8, v9 offset1:1
	s_waitcnt vmcnt(5)
	ds_write2_b32 v43, v10, v11 offset1:1
	ds_write2_b32 v44, v12, v13 offset1:1
	s_waitcnt vmcnt(4)
	ds_write2_b32 v45, v14, v15 offset1:1
	ds_write2_b32 v46, v16, v17 offset1:1
	s_waitcnt vmcnt(3)
	ds_write2_b32 v47, v18, v19 offset1:1
	ds_write2_b32 v48, v20, v21 offset1:1
	s_waitcnt vmcnt(2)
	ds_write2_b32 v49, v22, v23 offset1:1
	ds_write2_b32 v50, v24, v25 offset1:1
	s_waitcnt vmcnt(1)
	ds_write2_b32 v51, v26, v27 offset1:1
	ds_write2_b32 v52, v28, v29 offset1:1
	s_waitcnt vmcnt(0)
	ds_write2_b32 v53, v30, v31 offset1:1
	ds_write2_b32 v54, v32, v33 offset1:1
	s_waitcnt lgkmcnt(0)
	ds_read2_b32 v[2:3], v188 offset1:33
	s_waitcnt lgkmcnt(0)
	v_cvt_pk_bf16_f32 v2, v2, v3
	ds_read2_b32 v[4:5], v188 offset0:66 offset1:99
	v_or_b32_e32 v10, s10, v162
	s_waitcnt lgkmcnt(0)
	v_cvt_pk_bf16_f32 v3, v4, v5
	ds_read2_b32 v[4:5], v188 offset0:132 offset1:165
	v_lshl_add_u64 v[8:9], v[170:171], 0, s[6:7]
	v_lshlrev_b32_e32 v34, 11, v10
	s_waitcnt lgkmcnt(0)
	v_cvt_pk_bf16_f32 v4, v4, v5
	ds_read2_b32 v[6:7], v188 offset0:198 offset1:231
	s_waitcnt lgkmcnt(0)
	v_cvt_pk_bf16_f32 v5, v6, v7
	v_lshl_add_u64 v[10:11], v[8:9], 0, v[34:35]
	ds_read2_b32 v[6:7], v188 offset0:8 offset1:41
	global_store_dwordx4 v[10:11], v[2:5], off
	v_or_b32_e32 v10, s10, v185
	v_lshlrev_b32_e32 v34, 11, v10
	s_waitcnt lgkmcnt(0)
	v_cvt_pk_bf16_f32 v2, v6, v7
	ds_read2_b32 v[4:5], v188 offset0:74 offset1:107
	s_waitcnt lgkmcnt(0)
	v_cvt_pk_bf16_f32 v3, v4, v5
	ds_read2_b32 v[4:5], v188 offset0:140 offset1:173
	s_waitcnt lgkmcnt(0)
	v_cvt_pk_bf16_f32 v4, v4, v5
	ds_read2_b32 v[6:7], v188 offset0:206 offset1:239
	s_waitcnt lgkmcnt(0)
	v_cvt_pk_bf16_f32 v5, v6, v7
	v_lshl_add_u64 v[10:11], v[8:9], 0, v[34:35]
	ds_read2_b32 v[6:7], v188 offset0:16 offset1:49
	global_store_dwordx4 v[10:11], v[2:5], off
	v_or_b32_e32 v10, s10, v186
	v_lshlrev_b32_e32 v34, 11, v10
	s_waitcnt lgkmcnt(0)
	v_cvt_pk_bf16_f32 v2, v6, v7
	ds_read2_b32 v[4:5], v188 offset0:82 offset1:115
	s_waitcnt lgkmcnt(0)
	v_cvt_pk_bf16_f32 v3, v4, v5
	ds_read2_b32 v[4:5], v188 offset0:148 offset1:181
	s_waitcnt lgkmcnt(0)
	v_cvt_pk_bf16_f32 v4, v4, v5
	ds_read2_b32 v[6:7], v188 offset0:214 offset1:247
	s_waitcnt lgkmcnt(0)
	v_cvt_pk_bf16_f32 v5, v6, v7
	v_lshl_add_u64 v[10:11], v[8:9], 0, v[34:35]
	ds_read2_b32 v[6:7], v188 offset0:24 offset1:57
	global_store_dwordx4 v[10:11], v[2:5], off
	s_waitcnt lgkmcnt(0)
	s_nop 0
	v_cvt_pk_bf16_f32 v2, v6, v7
	ds_read2_b32 v[4:5], v188 offset0:90 offset1:123
	s_waitcnt lgkmcnt(0)
	v_cvt_pk_bf16_f32 v3, v4, v5
	ds_read2_b32 v[4:5], v188 offset0:156 offset1:189
	s_waitcnt lgkmcnt(0)
	v_cvt_pk_bf16_f32 v4, v4, v5
	v_or_b32_e32 v5, s10, v187
	ds_read2_b32 v[6:7], v188 offset0:222 offset1:255
	v_lshlrev_b32_e32 v34, 11, v5
	s_waitcnt lgkmcnt(0)
	v_cvt_pk_bf16_f32 v5, v6, v7
	v_lshl_add_u64 v[6:7], v[8:9], 0, v[34:35]
	global_store_dwordx4 v[6:7], v[2:5], off
	s_waitcnt lgkmcnt(0)

.LBB0_134:
	s_andn2_b64 vcc, exec, s[4:5]
	s_cbranch_vccnz .LBB0_91
	s_ashr_i32 s6, s50, 31
	s_mov_b64 s[4:5], s[0:1]
	s_lshr_b32 s6, s6, 26
	s_add_i32 s6, s50, s6
	s_load_dwordx2 s[4:5], s[4:5], 0x10
	s_and_b32 s10, s6, 0xffffffc0
	s_lshl_b32 s6, s6, 5
	s_and_b32 s6, s6, 0xfffff800
	s_sub_i32 s11, s18, s6
	v_add_u32_e32 v2, s11, v1
	v_or_b32_e32 v36, s10, v162
	v_ashrrev_i32_e32 v3, 31, v2
	v_ashrrev_i32_e32 v37, 31, v36
	v_or_b32_e32 v6, 8, v36
	s_waitcnt lgkmcnt(0)
	v_lshl_add_u64 v[2:3], v[2:3], 2, s[4:5]
	v_lshlrev_b64 v[4:5], 13, v[36:37]
	v_ashrrev_i32_e32 v7, 31, v6
	s_mov_b64 s[12:13], s[0:1]
	v_lshl_add_u64 v[4:5], v[2:3], 0, v[4:5]
	v_lshlrev_b64 v[6:7], 13, v[6:7]
	v_lshl_add_u64 v[6:7], v[2:3], 0, v[6:7]
	global_load_dwordx4 v[30:33], v[4:5], off nt
	global_load_dwordx4 v[26:29], v[6:7], off nt
	v_or_b32_e32 v4, 16, v36
	v_ashrrev_i32_e32 v5, 31, v4
	v_or_b32_e32 v6, 24, v36
	v_lshlrev_b64 v[4:5], 13, v[4:5]
	v_ashrrev_i32_e32 v7, 31, v6
	v_lshl_add_u64 v[4:5], v[2:3], 0, v[4:5]
	v_lshlrev_b64 v[6:7], 13, v[6:7]
	v_lshl_add_u64 v[6:7], v[2:3], 0, v[6:7]
	global_load_dwordx4 v[22:25], v[4:5], off nt
	global_load_dwordx4 v[18:21], v[6:7], off nt
	v_or_b32_e32 v4, 32, v36
	v_ashrrev_i32_e32 v5, 31, v4
	v_or_b32_e32 v6, 40, v36
	v_lshlrev_b64 v[4:5], 13, v[4:5]
	v_ashrrev_i32_e32 v7, 31, v6
	v_lshl_add_u64 v[4:5], v[2:3], 0, v[4:5]
	v_lshlrev_b64 v[6:7], 13, v[6:7]
	v_lshl_add_u64 v[6:7], v[2:3], 0, v[6:7]
	global_load_dwordx4 v[14:17], v[4:5], off nt
	global_load_dwordx4 v[10:13], v[6:7], off nt
	v_or_b32_e32 v4, 48, v36
	v_ashrrev_i32_e32 v5, 31, v4
	v_lshlrev_b64 v[4:5], 13, v[4:5]
	v_lshl_add_u64 v[56:57], v[2:3], 0, v[4:5]
	v_or_b32_e32 v4, 56, v36
	v_ashrrev_i32_e32 v5, 31, v4
	v_lshlrev_b64 v[4:5], 13, v[4:5]
	v_lshl_add_u64 v[58:59], v[2:3], 0, v[4:5]
	global_load_dwordx4 v[6:9], v[56:57], off nt
	global_load_dwordx4 v[2:5], v[58:59], off nt
	s_load_dwordx2 s[12:13], s[12:13], 0x8
	v_mov_b32_e32 v34, 1.0
	v_mov_b32_e32 v38, 1.0
	s_waitcnt lgkmcnt(0)
	s_cmp_lg_u64 s[12:13], 0
	s_cselect_b64 s[14:15], -1, 0
	s_cmp_eq_u64 s[12:13], 0
	s_cbranch_scc1 .LBB0_137
	s_ashr_i32 s11, s10, 31
	v_lshl_add_u64 v[36:37], v[36:37], 2, s[12:13]
	v_lshl_add_u64 v[56:57], s[10:11], 0, v[162:163]
	global_load_dword v36, v[36:37], off
	v_lshl_add_u64 v[56:57], v[56:57], 2, s[12:13]
	global_load_dword v38, v[56:57], off offset:32
	s_waitcnt vmcnt(1)
	v_pk_mul_f32 v[30:31], v[30:31], v[36:37] op_sel_hi:[1,0]
	v_pk_mul_f32 v[32:33], v[32:33], v[36:37] op_sel_hi:[1,0]
